# mixer_out: the per-element LDS waits that only covered the previous 2-byte store removed (gate values already in registers)
# speedup vs baseline: 1.0046x; 1.0046x over previous
; #define LAS __attribute__((address_space(3)))
; __device__ __forceinline__ void mixer_out_phase(const Ctx& X, LAS unsigned char* lds, int layer, int tid, int wave, int lane) {
;     ...
;     for (int u = blockIdx.x; u < 1536; u += gridDim.x) {
;         asm volatile("" : "+v"(lane), "+v"(tid));
;         LAS bf16_t* GT = opq((LAS bf16_t*)lds);
;         const int r = lane & 15, q = lane >> 4, h = wave >> 1, half = wave & 1;
;         const int mixer = u >> 9, rem = u & 511, b = rem >> 7, c = rem & 127;
;         const int uid = unit_id(mixer, b, h, c);
;         const int goff = mixer == 0 ? C_RG : (mixer == 1 ? C_GG : C_HG), moff = mixer == 0 ? 0 : (mixer == 1 ? 512 : 768);
;         const size_t row0 = (size_t)b * T + c * 64;
;         u32x4 gv[4];
; #pragma unroll
;         for (int n = 0; n < 4; ++n) { const int idx = tid + 512 * n; gv[n] = *(const u32x4*)(proj + (row0 + (idx >> 5)) * LDP + goff + (idx & 31) * 8); }
;         const bf16_t* qe = WSP(const bf16_t, WS_QEFF) + (size_t)uid * 4096;
;         const bf16_t* st = WSP(const bf16_t, WS_BCS) + (size_t)uid * 4096;
;         bf16x8 a[2][2], bb[4][2]; u32x4 ov[2][2];
; #pragma unroll
;         for (int rt = 0; rt < 2; ++rt) { const int rt4 = 2 * half + rt;
; #pragma unroll
;             for (int ks = 0; ks < 2; ++ks) a[rt][ks] = *(const bf16x8*)(qe + (16 * rt4 + r) * 64 + ks * 32 + q * 8);
;             const u32x4* ol = (const u32x4*)(WSP(const bf16_t, WS_OLOC) + ((size_t)uid * 4 + rt4) * 1024 + lane * 16); ov[rt][0] = ol[0]; ov[rt][1] = ol[1]; }
; #pragma unroll
;         for (int ct = 0; ct < 4; ++ct)
; #pragma unroll
;             for (int ks = 0; ks < 2; ++ks) { const bf16_t* tb = st + (size_t)((ct * 4 + 2 * ks + (q >> 1)) * 64) * 4;
;                 const u32x2 lo = *(const u32x2*)(tb + ((2 * (q & 1)) * 16 + r) * 4), hi = *(const u32x2*)(tb + ((2 * (q & 1) + 1) * 16 + r) * 4);
;                 bb[ct][ks] = __builtin_bit_cast(bf16x8, (u32x4){lo.x, lo.y, hi.x, hi.y}); }
;         const float* nw = mixer == 0 ? X.in[3] + layer * 256 + h * 64 : (mixer == 1 ? X.in[11] + layer * 64 : X.in[13] + layer * 64);
;         float wv[4];
; #pragma unroll
;         for (int ct = 0; ct < 4; ++ct) wv[ct] = nw[16 * ct + r];
; #pragma unroll
;         for (int n = 0; n < 4; ++n) { const int idx = tid + 512 * n; *(LAS u32x4*)(GT + (idx >> 5) * GP + (idx & 31) * 8) = gv[n]; }
;         LBAR();
.LBB0_888:
	s_ashr_i32 s6, s10, 9
	s_cmp_eq_u32 s6, 1
	s_movk_i32 s0, 0xd00
	s_cselect_b32 s7, 0x900, s0
	s_movk_i32 s0, 0x200
	s_cselect_b32 s11, s0, 0x300
	s_cselect_b32 s12, s50, s54
	s_cselect_b32 s13, s51, s55
	s_cmpk_lt_u32 s10, 0x200
	s_cselect_b64 s[0:1], -1, 0
	s_and_b64 s[0:1], s[0:1], exec
	s_cselect_b32 s11, 0, s11
	s_add_u32 s12, s12, s4
	s_addc_u32 s13, s13, s5
	s_cmpk_lt_u32 s10, 0x200
	s_cselect_b64 vcc, -1, 0
	s_and_b64 s[0:1], vcc, exec
	s_cselect_b32 s7, 0x300, s7
	s_cselect_b32 s1, s9, s13
	s_cselect_b32 s0, s8, s12
	s_bfe_u32 s12, s10, 0x20007
	s_and_b32 s13, s10, 0x7f
	s_lshl_b32 s14, s12, 9
	s_lshl_b32 s15, s6, 11
	s_lshl_b32 s6, s12, 13
	s_lshl_b32 s12, s13, 6
	s_or_b32 s16, s6, s12
	s_lshl_b32 s6, s7, 1
	s_add_u32 s6, s76, s6
	s_waitcnt vmcnt(0)
	v_lshlrev_b32_e32 v6, 4, v104
	v_ashrrev_i32_e32 v94, 5, v104
	s_addc_u32 s7, s77, 0
	v_and_b32_e32 v156, 0x1f0, v6
	v_ashrrev_i32_e32 v95, 31, v94
	v_lshl_add_u64 v[6:7], s[6:7], 0, v[156:157]
	v_lshl_add_u64 v[92:93], s[16:17], 0, v[94:95]
	v_mov_b32_e32 v108, v157
	v_mad_i64_i32 v[8:9], s[6:7], v92, s71, v[6:7]
	global_load_dwordx4 v[62:65], v[8:9], off
	v_add_u32_e32 v8, 0x200, v104
	v_ashrrev_i32_e32 v98, 5, v8
	v_ashrrev_i32_e32 v99, 31, v98
	v_lshl_add_u64 v[90:91], s[16:17], 0, v[98:99]
	v_mad_i64_i32 v[8:9], s[6:7], v90, s71, v[6:7]
	global_load_dwordx4 v[74:77], v[8:9], off
	v_add_u32_e32 v8, 0x400, v104
	v_ashrrev_i32_e32 v100, 5, v8
	v_ashrrev_i32_e32 v101, 31, v100
	v_lshl_add_u64 v[88:89], s[16:17], 0, v[100:101]
	v_mad_i64_i32 v[8:9], s[6:7], v88, s71, v[6:7]
	global_load_dwordx4 v[78:81], v[8:9], off
	v_add_u32_e32 v8, 0x600, v104
	v_ashrrev_i32_e32 v102, 5, v8
	v_ashrrev_i32_e32 v103, 31, v102
	v_lshl_add_u64 v[86:87], s[16:17], 0, v[102:103]
	v_mad_i64_i32 v[6:7], s[6:7], v86, s71, v[6:7]
	s_or_b32 s6, s13, s23
	s_add_i32 s6, s6, s15
	s_add_i32 s6, s6, s14
	s_ashr_i32 s7, s6, 31
	s_waitcnt vmcnt(14)
	v_ashrrev_i32_e32 v110, 4, v105
	s_lshl_b64 s[6:7], s[6:7], 13
	global_load_dwordx4 v[82:85], v[6:7], off
	s_add_u32 s12, s89, s6
	v_lshlrev_b32_e32 v6, 3, v110
	s_addc_u32 s13, s78, s7
	v_ashrrev_i32_e32 v7, 31, v6
	v_and_b32_e32 v109, 15, v105
	v_lshl_add_u64 v[6:7], v[6:7], 1, s[12:13]
	s_add_u32 s12, s19, s6
	s_addc_u32 s13, s20, s7
	s_lshl_b32 s16, s21, 1
	v_lshlrev_b32_e32 v22, 7, v110
	v_lshlrev_b32_e32 v95, 2, v109
	s_add_u32 s6, s74, s6
	v_and_or_b32 v22, v22, s33, v95
	s_addc_u32 s7, s75, s7
	v_lshlrev_b32_e32 v22, 1, v22
	v_mov_b32_e32 v23, v157
	v_lshlrev_b32_e32 v12, 6, v109
	v_lshlrev_b32_e32 v8, 4, v105
	v_lshl_add_u64 v[50:51], s[6:7], 0, v[22:23]
	v_lshlrev_b32_e32 v22, 1, v105
	v_ashrrev_i32_e32 v9, 31, v8
	v_or_b32_e32 v10, s21, v12
	v_and_b32_e32 v52, 0xffffffc0, v22
	v_lshl_add_u64 v[8:9], v[8:9], 1, s[12:13]
	v_lshlrev_b32_e32 v10, 1, v10
	v_mov_b32_e32 v11, v157
	v_add_u32_e32 v26, 0x80, v52
	v_add_u32_e32 v30, 0x100, v52
	v_lshl_add_u64 v[10:11], v[6:7], 0, v[10:11]
	v_lshl_add_u64 v[18:19], v[8:9], 0, s[16:17]
	v_add_lshl_u32 v8, v12, s21, 1
	v_mov_b32_e32 v9, v157
	v_ashrrev_i32_e32 v53, 31, v52
	v_ashrrev_i32_e32 v27, 31, v26
	v_ashrrev_i32_e32 v31, 31, v30
	global_load_dwordx4 v[66:69], v[10:11], off
	global_load_dwordx4 v[70:73], v[10:11], off offset:64
	global_load_dwordx4 v[54:57], v[18:19], off offset:16
	global_load_dwordx4 v[58:61], v[18:19], off
	v_lshl_add_u64 v[10:11], v[6:7], 0, v[8:9]
	s_waitcnt vmcnt(12)
	v_lshl_add_u64 v[24:25], v[52:53], 3, v[50:51]
	v_lshl_add_u64 v[28:29], v[26:27], 3, v[50:51]
	v_lshl_add_u64 v[32:33], v[30:31], 3, v[50:51]
	global_load_dwordx4 v[6:9], v[10:11], off offset:2048
	s_nop 0
	global_load_dwordx4 v[10:13], v[10:11], off offset:2112
	s_nop 0
	global_load_dwordx4 v[14:17], v[18:19], off offset:2064
	s_nop 0
	global_load_dwordx4 v[18:21], v[18:19], off offset:2048
	s_nop 0
	global_load_dwordx2 v[22:23], v[24:25], off
	s_nop 0
	global_load_dwordx2 v[24:25], v[24:25], off offset:128
	s_nop 0
	global_load_dwordx2 v[26:27], v[28:29], off
	s_nop 0
	global_load_dwordx2 v[28:29], v[28:29], off offset:128
	s_nop 0
	global_load_dwordx2 v[30:31], v[32:33], off
	s_nop 0
	global_load_dwordx2 v[32:33], v[32:33], off offset:128
	v_add_u32_e32 v34, 0x180, v52
	v_add_u32_e32 v38, 0x200, v52
	v_add_u32_e32 v42, 0x280, v52
	v_add_u32_e32 v46, 0x300, v52
	v_ashrrev_i32_e32 v35, 31, v34
	v_ashrrev_i32_e32 v39, 31, v38
	v_ashrrev_i32_e32 v43, 31, v42
	v_ashrrev_i32_e32 v47, 31, v46
	v_lshl_add_u64 v[36:37], v[34:35], 3, v[50:51]
	v_lshl_add_u64 v[40:41], v[38:39], 3, v[50:51]
	v_lshl_add_u64 v[44:45], v[42:43], 3, v[50:51]
	v_lshl_add_u64 v[48:49], v[46:47], 3, v[50:51]
	global_load_dwordx2 v[34:35], v[36:37], off
	s_nop 0
	global_load_dwordx2 v[36:37], v[36:37], off offset:128
	s_nop 0
	global_load_dwordx2 v[38:39], v[40:41], off
	s_nop 0
	global_load_dwordx2 v[40:41], v[40:41], off offset:128
	s_nop 0
	global_load_dwordx2 v[42:43], v[44:45], off
	s_nop 0
	global_load_dwordx2 v[44:45], v[44:45], off offset:128
	s_nop 0
	global_load_dwordx2 v[46:47], v[48:49], off
	s_nop 0
	global_load_dwordx2 v[48:49], v[48:49], off offset:128
	v_add_u32_e32 v52, 0x380, v52
	v_ashrrev_i32_e32 v53, 31, v52
	v_lshl_add_u64 v[52:53], v[52:53], 3, v[50:51]
	global_load_dwordx2 v[50:51], v[52:53], off
	s_nop 0
	global_load_dwordx2 v[52:53], v[52:53], off offset:128
	v_add_u32_e32 v112, v108, v156
	global_load_dword v106, v95, s[0:1]
	global_load_dword v103, v95, s[0:1] offset:64
	global_load_dword v101, v95, s[0:1] offset:128
	global_load_dword v99, v95, s[0:1] offset:192
	v_mad_u64_u32 v[96:97], s[0:1], v94, s34, v[112:113]
	s_waitcnt vmcnt(31)
	ds_write_b128 v96, v[62:65]
	v_mad_u64_u32 v[94:95], s[0:1], v98, s34, v[112:113]
	v_and_b32_e32 v63, 64, v230
	s_waitcnt vmcnt(30)
	ds_write_b128 v94, v[74:77]
	v_mad_u64_u32 v[76:77], s[0:1], v100, s34, v[112:113]
	v_mad_u64_u32 v[74:75], s[0:1], v102, s34, v[112:113]
	v_xor_b32_e32 v62, 1, v230
	v_add_u32_e32 v63, 64, v63
	v_cmp_lt_i32_e64 s[0:1], v62, v63
	s_waitcnt vmcnt(29)
	ds_write_b128 v76, v[78:81]
	s_waitcnt vmcnt(28)
	ds_write_b128 v74, v[82:85]
	v_cndmask_b32_e64 v62, v230, v62, s[0:1]
	v_lshlrev_b32_e32 v75, 2, v62
	v_xor_b32_e32 v62, 2, v230
	v_cmp_lt_i32_e64 s[0:1], v62, v63
	v_lshl_add_u32 v84, v110, 2, s22
	v_add_u32_e32 v85, s23, v108
	v_cndmask_b32_e64 v62, v230, v62, s[0:1]
	v_lshlrev_b32_e32 v77, 2, v62
	v_xor_b32_e32 v62, 4, v230
	v_cmp_lt_i32_e64 s[0:1], v62, v63
	v_lshlrev_b32_e32 v95, 1, v109
	v_cndmask_b32_e32 v107, v225, v229, vcc
	v_cndmask_b32_e64 v62, v230, v62, s[0:1]
	v_lshlrev_b32_e32 v78, 2, v62
	v_xor_b32_e32 v62, 8, v230
	v_cmp_lt_i32_e64 s[0:1], v62, v63
	s_waitcnt lgkmcnt(0)
	s_barrier
; #define LAS __attribute__((address_space(3)))
; __device__ __forceinline__ float bf_lo(unsigned u) { return __uint_as_float(u << 16); }
; __device__ __forceinline__ float bf_hi(unsigned u) { return __uint_as_float(u & 0xffff0000u); }
; __device__ __forceinline__ float bf2f(bf16_t b) { return __uint_as_float((unsigned)b << 16); }
; __device__ __forceinline__ void mixer_out_phase(const Ctx& X, LAS unsigned char* lds, int layer, int tid, int wave, int lane) {
;     ...
;         LBAR();
;         const bool on = ((MIX_MASK >> (mixer == 0 ? 0 : (mixer == 1 ? 2 : 3))) & 1) != 0;
; #pragma unroll
;         for (int rt = 0; rt < 2; ++rt) {
;             f32x4 acc[4];
;             acc[0] = (f32x4){bf_lo(ov[rt][0].x), bf_hi(ov[rt][0].x), bf_lo(ov[rt][0].y), bf_hi(ov[rt][0].y)}; acc[1] = (f32x4){bf_lo(ov[rt][0].z), bf_hi(ov[rt][0].z), bf_lo(ov[rt][0].w), bf_hi(ov[rt][0].w)};
;             acc[2] = (f32x4){bf_lo(ov[rt][1].x), bf_hi(ov[rt][1].x), bf_lo(ov[rt][1].y), bf_hi(ov[rt][1].y)}; acc[3] = (f32x4){bf_lo(ov[rt][1].z), bf_hi(ov[rt][1].z), bf_lo(ov[rt][1].w), bf_hi(ov[rt][1].w)};
; #pragma unroll
;             for (int ct = 0; ct < 4; ++ct)
; #pragma unroll
;                 for (int ks = 0; ks < 2; ++ks) acc[ct] = __builtin_amdgcn_mfma_f32_16x16x32_bf16(a[rt][ks], bb[ct][ks], acc[ct], 0, 0, 0);
; #pragma unroll
;             for (int j = 0; j < 4; ++j) {
;                 float sm = (acc[0][j] + acc[1][j]) + (acc[2][j] + acc[3][j]);
;                 sm += __shfl_xor(sm, 1); sm += __shfl_xor(sm, 2); sm += __shfl_xor(sm, 4); sm += __shfl_xor(sm, 8);
;                 const float mu = mixer == 0 ? sm * (1.f / 64.f) : 0.f;
;                 float d[4], s2 = 0.f;
; #pragma unroll
;                 for (int ct = 0; ct < 4; ++ct) { d[ct] = acc[ct][j] - mu; s2 += d[ct] * d[ct]; }
;                 s2 += __shfl_xor(s2, 1); s2 += __shfl_xor(s2, 2); s2 += __shfl_xor(s2, 4); s2 += __shfl_xor(s2, 8);
;                 const float rs = rsqrtf(s2 * (1.f / 64.f) + (mixer == 0 ? 1e-5f : 1e-6f));
;                 const int ii = 16 * (2 * half + rt) + 4 * q + j;
; #pragma unroll
;                 for (int ct = 0; ct < 4; ++ct) { LAS bf16_t* gp = GT + ii * GP + h * 64 + 16 * ct + r;
;                     const float y = d[ct] * rs * wv[ct] * silu_acc(bf2f(*gp));
;                     *gp = on ? f2bf(y) : (bf16_t)0; }
	v_mul_lo_u32 v146, v84, s34
	v_add3_u32 v146, v85, v95, v146
	ds_read_u16 v134, v146
	ds_read_u16 v135, v146 offset:32
	ds_read_u16 v136, v146 offset:64
	ds_read_u16 v137, v146 offset:96
	ds_read_u16 v138, v146 offset:528
	ds_read_u16 v139, v146 offset:560
	ds_read_u16 v140, v146 offset:592
	ds_read_u16 v141, v146 offset:624
	ds_read_u16 v142, v146 offset:1056
	ds_read_u16 v143, v146 offset:1088
	ds_read_u16 v144, v146 offset:1120
	ds_read_u16 v145, v146 offset:1152
	ds_read_u16 v147, v146 offset:1584
	ds_read_u16 v148, v146 offset:1616
	ds_read_u16 v149, v146 offset:1648
	ds_read_u16 v150, v146 offset:1680
	ds_read_u16 v151, v146 offset:8448
	ds_read_u16 v152, v146 offset:8480
	ds_read_u16 v153, v146 offset:8512
	ds_read_u16 v154, v146 offset:8544
	ds_read_u16 v155, v146 offset:8976
	ds_read_u16 v182, v146 offset:9008
	ds_read_u16 v183, v146 offset:9040
	ds_read_u16 v184, v146 offset:9072
	ds_read_u16 v185, v146 offset:9504
	ds_read_u16 v186, v146 offset:9536
	ds_read_u16 v187, v146 offset:9568
	ds_read_u16 v188, v146 offset:9600
	ds_read_u16 v189, v146 offset:10032
	ds_read_u16 v190, v146 offset:10064
	ds_read_u16 v191, v146 offset:10096
	ds_read_u16 v192, v146 offset:10128
	s_waitcnt vmcnt(25)
	v_lshlrev_b32_e32 v80, 16, v54
	v_cndmask_b32_e64 v62, v230, v62, s[0:1]
	v_lshlrev_b32_e32 v79, 2, v62
	s_waitcnt vmcnt(24)
	v_lshlrev_b32_e32 v62, 16, v58
	v_and_b32_e32 v63, 0xffff0000, v58
	v_lshlrev_b32_e32 v64, 16, v59
	v_and_b32_e32 v65, 0xffff0000, v59
	v_lshlrev_b32_e32 v58, 16, v60
	v_and_b32_e32 v59, 0xffff0000, v60
	v_lshlrev_b32_e32 v60, 16, v61
	v_and_b32_e32 v61, 0xffff0000, v61
	v_and_b32_e32 v81, 0xffff0000, v54
	v_lshlrev_b32_e32 v82, 16, v55
	s_waitcnt vmcnt(14)
	v_mfma_f32_16x16x32_bf16 v[58:61], v[66:69], v[30:33], v[58:61]
	v_and_b32_e32 v83, 0xffff0000, v55
	v_lshlrev_b32_e32 v108, 16, v56
	v_and_b32_e32 v109, 0xffff0000, v56
	v_lshlrev_b32_e32 v110, 16, v57
	v_and_b32_e32 v111, 0xffff0000, v57
	v_mfma_f32_16x16x32_bf16 v[54:57], v[66:69], v[22:25], v[62:65]
	s_waitcnt vmcnt(12)
	v_mfma_f32_16x16x32_bf16 v[62:65], v[70:73], v[34:37], v[58:61]
	s_waitcnt vmcnt(10)
	v_mfma_f32_16x16x32_bf16 v[58:61], v[66:69], v[38:41], v[80:83]
	s_waitcnt vmcnt(6)
	v_mfma_f32_16x16x32_bf16 v[66:69], v[66:69], v[46:49], v[108:111]
	v_mfma_f32_16x16x32_bf16 v[54:57], v[70:73], v[26:29], v[54:57]
	v_mfma_f32_16x16x32_bf16 v[58:61], v[70:73], v[42:45], v[58:61]
	s_waitcnt vmcnt(4)
	v_mfma_f32_16x16x32_bf16 v[66:69], v[70:73], v[50:53], v[66:69]
	s_nop 4
	v_mov_b32_e32 v70, v54
	v_mov_b32_e32 v71, v58
	v_mov_b32_e32 v72, v62
	v_mov_b32_e32 v83, v58
	v_mov_b32_e32 v73, v66
	v_pk_add_f32 v[70:71], v[70:71], v[72:73]
	v_mov_b32_e32 v72, v54
	v_add_f32_e32 v70, v70, v71
	s_nop 1
	v_mov_b32_e32 v73, v62
	v_mov_b32_e32 v82, v66
	s_waitcnt lgkmcnt(0)
	v_add_f32_dpp v70, v70, v70 quad_perm:[1,0,3,2] row_mask:0xf bank_mask:0xf
	s_nop 1
	s_waitcnt lgkmcnt(0)
	v_add_f32_dpp v70, v70, v70 quad_perm:[2,3,0,1] row_mask:0xf bank_mask:0xf
	s_nop 1
	s_waitcnt lgkmcnt(0)
	v_add_f32_dpp v70, v70, v70 row_half_mirror row_mask:0xf bank_mask:0xf
	s_nop 1
	s_waitcnt lgkmcnt(0)
	v_add_f32_dpp v70, v70, v70 row_mirror row_mask:0xf bank_mask:0xf
	v_mul_f32_e32 v70, 0x3c800000, v70
	v_cndmask_b32_e32 v70, 0, v70, vcc
	v_pk_add_f32 v[72:73], v[72:73], v[70:71] op_sel_hi:[1,0] neg_lo:[0,1] neg_hi:[0,1]
	v_pk_add_f32 v[70:71], v[82:83], v[70:71] op_sel_hi:[1,0] neg_lo:[0,1] neg_hi:[0,1]
	v_pk_mul_f32 v[80:81], v[72:73], v[72:73]
	v_pk_mul_f32 v[82:83], v[70:71], v[70:71]
	v_add_f32_e32 v54, v80, v81
	v_add_f32_e32 v54, v83, v54
	v_add_f32_e32 v54, v82, v54
	s_nop 1
	s_waitcnt lgkmcnt(0)
	v_add_f32_dpp v54, v54, v54 quad_perm:[1,0,3,2] row_mask:0xf bank_mask:0xf
	s_nop 1
	s_waitcnt lgkmcnt(0)
	v_add_f32_dpp v54, v54, v54 quad_perm:[2,3,0,1] row_mask:0xf bank_mask:0xf
	s_nop 1
	s_waitcnt lgkmcnt(0)
	v_add_f32_dpp v54, v54, v54 row_half_mirror row_mask:0xf bank_mask:0xf
	s_nop 1
	s_waitcnt lgkmcnt(0)
	v_add_f32_dpp v54, v54, v54 row_mirror row_mask:0xf bank_mask:0xf
	v_fmamk_f32 v54, v54, 0x3c800000, v107
	v_cmp_gt_f32_e64 s[0:1], s3, v54
	v_mul_f32_e32 v58, 0x4b800000, v54
	s_nop 0
	v_cndmask_b32_e64 v54, v54, v58, s[0:1]
	v_rsq_f32_e32 v54, v54
	s_nop 0
	v_mul_f32_e32 v58, 0x45800000, v54
	v_cndmask_b32_e64 v58, v54, v58, s[0:1]
	v_mul_lo_u32 v54, v84, s34
	v_add3_u32 v54, v85, v95, v54
	v_mov_b32_e32 v62, v134
	s_nop 0
	s_nop 0
	v_lshlrev_b32_e32 v62, 16, v62
	v_mul_f32_e32 v66, 0xbfb8aa3b, v62
	v_exp_f32_e32 v66, v66
	s_nop 0
	v_add_f32_e32 v66, 1.0, v66
	v_rcp_f32_e32 v66, v66
	s_nop 0
	v_mul_f32_e32 v62, v66, v62
	v_mul_f32_e32 v66, v72, v58
	s_waitcnt vmcnt(3)
	v_mul_f32_e32 v66, v106, v66
	v_mul_f32_e32 v62, v62, v66
	v_cvt_pk_bf16_f32 v62, v62, v157
	ds_write_b16 v54, v62
	v_mov_b32_e32 v62, v135
	s_nop 0
	s_nop 0
	v_lshlrev_b32_e32 v62, 16, v62
	v_mul_f32_e32 v66, 0xbfb8aa3b, v62
	v_exp_f32_e32 v66, v66
	s_nop 0
	v_add_f32_e32 v66, 1.0, v66
	v_rcp_f32_e32 v66, v66
	s_nop 0
	v_mul_f32_e32 v62, v66, v62
	v_mul_f32_e32 v66, v73, v58
	s_waitcnt vmcnt(2)
	v_mul_f32_e32 v66, v103, v66
	v_mul_f32_e32 v62, v62, v66
	v_cvt_pk_bf16_f32 v62, v62, v157
	ds_write_b16 v54, v62 offset:32
	v_mov_b32_e32 v62, v136
	s_nop 0
	s_nop 0
	v_lshlrev_b32_e32 v62, 16, v62
	v_mul_f32_e32 v66, 0xbfb8aa3b, v62
	v_exp_f32_e32 v66, v66
	s_nop 0
	v_add_f32_e32 v66, 1.0, v66
	v_rcp_f32_e32 v66, v66
	s_nop 0
	v_mul_f32_e32 v62, v66, v62
	v_mul_f32_e32 v66, v71, v58
	s_waitcnt vmcnt(1)
	v_mul_f32_e32 v66, v101, v66
	v_mul_f32_e32 v62, v62, v66
	v_cvt_pk_bf16_f32 v62, v62, v157
	ds_write_b16 v54, v62 offset:64
	v_mov_b32_e32 v62, v137
	s_nop 0
	v_mul_f32_e32 v58, v70, v58
	s_waitcnt vmcnt(0)
	s_add_i32 s98, s10, s18
	s_cmpk_ge_u32 s98, 0x600
	s_cbranch_scc1 .LpfO_done
	s_lshr_b32 s99, s98, 9
	s_and_b32 s98, s98, 0x1ff
	s_lshr_b32 s100, s98, 7
	s_and_b32 s98, s98, 0x7f
	s_lshl_b32 s101, s99, 2
	s_add_u32 s101, s101, s100
	s_lshl_b32 s101, s101, 9
	s_add_u32 s101, s101, s98
	s_lshl_b32 s101, s101, 13
	s_cmp_eq_u32 s99, 2
	s_mul_i32 s99, s99, 0xc00
	s_cselect_b32 s32, 0x400, 0
	s_sub_u32 s99, s99, s32
	s_add_u32 s99, s99, 0x600
	s_lshl_b32 s100, s100, 13
	s_lshl_b32 s98, s98, 6
	s_add_u32 s98, s98, s100
	s_mul_i32 s98, s98, 0x1c00
	s_add_u32 s98, s98, s99
	v_and_b32_e32 v237, 0xff, v224
	v_lshrrev_b32_e32 v238, 2, v237
	v_and_b32_e32 v239, 3, v237
	v_lshlrev_b32_e32 v239, 7, v239
	v_mad_u32_u24 v238, v238, s71, v239
	v_lshrrev_b32_e32 v239, 6, v237
	v_and_b32_e32 v237, 63, v237
	v_lshlrev_b32_e32 v239, 20, v239
	v_lshl_or_b32 v237, v237, 7, v239
	v_readfirstlane_b32 s32, v224
	s_add_u32 s82, s76, s98
	s_addc_u32 s83, s77, 0
	s_cmpk_lt_u32 s32, 0x100
	s_cbranch_scc0 .LpfO_hi
	s_add_u32 s98, s101, 0x3500000
	s_add_u32 s98, s30, s98
	s_addc_u32 s99, s31, 0
	global_load_dword v234, v238, s[82:83]
	global_load_dword v234, v237, s[98:99]
	s_branch .LpfO_done

; #define LAS __attribute__((address_space(3)))
; __device__ __forceinline__ float bf2f(bf16_t b) { return __uint_as_float((unsigned)b << 16); }
; __device__ __forceinline__ bf16_t f2bf(float f) { return (bf16_t)(pk2(f, 0.f) & 0xffffu); }
; __device__ __forceinline__ float silu_acc(float x) { return x * frcp(1.0f + fexp(-x)); }
; __device__ __forceinline__ void mixer_out_phase(const Ctx& X, LAS unsigned char* lds, int layer, int tid, int wave, int lane) {
;     ...
;             for (int j = 0; j < 4; ++j) {
;                 float sm = (acc[0][j] + acc[1][j]) + (acc[2][j] + acc[3][j]);
;                 sm += __shfl_xor(sm, 1); sm += __shfl_xor(sm, 2); sm += __shfl_xor(sm, 4); sm += __shfl_xor(sm, 8);
;                 const float mu = mixer == 0 ? sm * (1.f / 64.f) : 0.f;
;                 float d[4], s2 = 0.f;
; #pragma unroll
;                 for (int ct = 0; ct < 4; ++ct) { d[ct] = acc[ct][j] - mu; s2 += d[ct] * d[ct]; }
;                 s2 += __shfl_xor(s2, 1); s2 += __shfl_xor(s2, 2); s2 += __shfl_xor(s2, 4); s2 += __shfl_xor(s2, 8);
;                 const float rs = rsqrtf(s2 * (1.f / 64.f) + (mixer == 0 ? 1e-5f : 1e-6f));
;                 const int ii = 16 * (2 * half + rt) + 4 * q + j;
; #pragma unroll
;                 for (int ct = 0; ct < 4; ++ct) { LAS bf16_t* gp = GT + ii * GP + h * 64 + 16 * ct + r;
;                     const float y = d[ct] * rs * wv[ct] * silu_acc(bf2f(*gp));
;                     *gp = on ? f2bf(y) : (bf16_t)0; }
.LpfO_done:
	v_mul_f32_e32 v58, v99, v58
	s_waitcnt lgkmcnt(0)
	v_lshlrev_b32_e32 v62, 16, v62
	v_mul_f32_e32 v66, 0xbfb8aa3b, v62
	v_exp_f32_e32 v66, v66
	s_nop 0
	v_add_f32_e32 v66, 1.0, v66
	v_rcp_f32_e32 v66, v66
	s_nop 0
	v_mul_f32_e32 v62, v66, v62
	v_mul_f32_e32 v58, v62, v58
	v_cvt_pk_bf16_f32 v58, v58, v157
	ds_write_b16 v54, v58 offset:96
	v_mov_b32_e32 v58, v55
	v_mov_b32_e32 v66, v63
	v_pk_add_f32 v[70:71], v[58:59], v[66:67]
	s_nop 0
	v_add_f32_e32 v58, v70, v71
	s_nop 1
	s_waitcnt lgkmcnt(0)
	v_add_f32_dpp v58, v58, v58 quad_perm:[1,0,3,2] row_mask:0xf bank_mask:0xf
	s_nop 1
	s_waitcnt lgkmcnt(0)
	v_add_f32_dpp v58, v58, v58 quad_perm:[2,3,0,1] row_mask:0xf bank_mask:0xf
	s_nop 1
	s_waitcnt lgkmcnt(0)
	v_add_f32_dpp v58, v58, v58 row_half_mirror row_mask:0xf bank_mask:0xf
	s_nop 1
	s_waitcnt lgkmcnt(0)
	v_add_f32_dpp v58, v58, v58 row_mirror row_mask:0xf bank_mask:0xf
	v_mul_f32_e32 v58, 0x3c800000, v58
	v_cndmask_b32_e32 v66, 0, v58, vcc
	v_mov_b32_e32 v62, v55
	v_pk_add_f32 v[62:63], v[62:63], v[66:67] op_sel_hi:[1,0] neg_lo:[0,1] neg_hi:[0,1]
	v_mov_b32_e32 v58, v67
	v_pk_mul_f32 v[70:71], v[62:63], v[62:63]
	v_pk_add_f32 v[58:59], v[58:59], v[66:67] op_sel_hi:[1,0] neg_lo:[0,1] neg_hi:[0,1]
	v_add_f32_e32 v55, v70, v71
	v_pk_mul_f32 v[66:67], v[58:59], v[58:59]
	v_mov_b32_e32 v70, v68
	v_add_f32_e32 v55, v67, v55
	v_add_f32_e32 v55, v66, v55
	s_nop 1
	v_mov_b32_e32 v71, v60
	s_waitcnt lgkmcnt(0)
	v_add_f32_dpp v55, v55, v55 quad_perm:[1,0,3,2] row_mask:0xf bank_mask:0xf
	s_nop 1
	s_waitcnt lgkmcnt(0)
	v_add_f32_dpp v55, v55, v55 quad_perm:[2,3,0,1] row_mask:0xf bank_mask:0xf
	s_nop 1
	s_waitcnt lgkmcnt(0)
	v_add_f32_dpp v55, v55, v55 row_half_mirror row_mask:0xf bank_mask:0xf
	s_nop 1
	s_waitcnt lgkmcnt(0)
	v_add_f32_dpp v55, v55, v55 row_mirror row_mask:0xf bank_mask:0xf
	v_fmamk_f32 v55, v55, 0x3c800000, v107
	v_cmp_gt_f32_e64 s[0:1], s3, v55
	v_mul_f32_e32 v66, 0x4b800000, v55
	s_nop 0
	v_cndmask_b32_e64 v55, v55, v66, s[0:1]
	v_rsq_f32_e32 v55, v55
	s_nop 0
	v_mul_f32_e32 v66, 0x45800000, v55
	v_cndmask_b32_e64 v55, v55, v66, s[0:1]
	v_mov_b32_e32 v66, v138
	s_nop 0
	v_mul_f32_e32 v62, v62, v55
	v_mul_f32_e32 v62, v106, v62
	v_mul_f32_e32 v63, v63, v55
	v_mul_f32_e32 v63, v103, v63
	s_nop 0
	v_lshlrev_b32_e32 v66, 16, v66
	v_mul_f32_e32 v67, 0xbfb8aa3b, v66
	v_exp_f32_e32 v67, v67
	v_mul_f32_e32 v59, v59, v55
	v_mul_f32_e32 v59, v101, v59
	v_mul_f32_e32 v55, v58, v55
	v_add_f32_e32 v67, 1.0, v67
	v_rcp_f32_e32 v67, v67
	v_mul_f32_e32 v55, v99, v55
	v_mov_b32_e32 v58, v56
	v_mul_f32_e32 v66, v67, v66
	v_mul_f32_e32 v62, v66, v62
	v_cvt_pk_bf16_f32 v62, v62, v157
	ds_write_b16 v54, v62 offset:528
	v_mov_b32_e32 v62, v139
	s_nop 0
	s_nop 0
	v_lshlrev_b32_e32 v62, 16, v62
	v_mul_f32_e32 v66, 0xbfb8aa3b, v62
	v_exp_f32_e32 v66, v66
	s_nop 0
	v_add_f32_e32 v66, 1.0, v66
	v_rcp_f32_e32 v66, v66
	s_nop 0
	v_mul_f32_e32 v62, v66, v62
	v_mul_f32_e32 v62, v62, v63
	v_cvt_pk_bf16_f32 v62, v62, v157
	ds_write_b16 v54, v62 offset:560
	v_mov_b32_e32 v62, v140
	s_nop 0
	s_nop 0
	v_lshlrev_b32_e32 v62, 16, v62
	v_mul_f32_e32 v63, 0xbfb8aa3b, v62
	v_exp_f32_e32 v63, v63
	s_nop 0
	v_add_f32_e32 v63, 1.0, v63
	v_rcp_f32_e32 v63, v63
	s_nop 0
	v_mul_f32_e32 v62, v63, v62
	v_mul_f32_e32 v59, v62, v59
	v_cvt_pk_bf16_f32 v59, v59, v157
	ds_write_b16 v54, v59 offset:592
	v_mov_b32_e32 v59, v141
	s_nop 0
	v_mov_b32_e32 v63, v68
	v_mov_b32_e32 v68, v65
	s_nop 0
	v_lshlrev_b32_e32 v59, 16, v59
	v_mul_f32_e32 v62, 0xbfb8aa3b, v59
	v_exp_f32_e32 v62, v62
	s_nop 0
	v_add_f32_e32 v62, 1.0, v62
	v_rcp_f32_e32 v62, v62
	s_nop 0
	v_mul_f32_e32 v59, v62, v59
	v_mul_f32_e32 v55, v55, v59
	v_mov_b32_e32 v59, v60
	v_mov_b32_e32 v62, v64
	v_cvt_pk_bf16_f32 v55, v55, v157
	v_pk_add_f32 v[58:59], v[58:59], v[62:63]
	ds_write_b16 v54, v55 offset:624
	v_add_f32_e32 v55, v58, v59
	s_nop 1
	v_mov_b32_e32 v62, v56
	v_mov_b32_e32 v63, v64
	v_mov_b32_e32 v64, v57
	s_waitcnt lgkmcnt(0)
	v_add_f32_dpp v55, v55, v55 quad_perm:[1,0,3,2] row_mask:0xf bank_mask:0xf
	s_nop 1
	s_waitcnt lgkmcnt(0)
	v_add_f32_dpp v55, v55, v55 quad_perm:[2,3,0,1] row_mask:0xf bank_mask:0xf
	s_nop 1
	s_waitcnt lgkmcnt(0)
	v_add_f32_dpp v55, v55, v55 row_half_mirror row_mask:0xf bank_mask:0xf
	s_nop 1
	s_waitcnt lgkmcnt(0)
	v_add_f32_dpp v55, v55, v55 row_mirror row_mask:0xf bank_mask:0xf
	v_mul_f32_e32 v55, 0x3c800000, v55
	v_cndmask_b32_e32 v58, 0, v55, vcc
	v_pk_add_f32 v[62:63], v[62:63], v[58:59] op_sel_hi:[1,0] neg_lo:[0,1] neg_hi:[0,1]
	v_pk_add_f32 v[58:59], v[70:71], v[58:59] op_sel_hi:[1,0] neg_lo:[0,1] neg_hi:[0,1]
	v_pk_mul_f32 v[66:67], v[62:63], v[62:63]
	v_pk_mul_f32 v[70:71], v[58:59], v[58:59]
	v_add_f32_e32 v55, v66, v67
	v_add_f32_e32 v55, v71, v55
	v_add_f32_e32 v55, v70, v55
	s_nop 1
	v_lshlrev_b32_e32 v66, 16, v17
	v_and_b32_e32 v67, 0xffff0000, v17
	s_waitcnt lgkmcnt(0)
	v_add_f32_dpp v55, v55, v55 quad_perm:[1,0,3,2] row_mask:0xf bank_mask:0xf
	s_nop 1
	s_waitcnt lgkmcnt(0)
	v_add_f32_dpp v55, v55, v55 quad_perm:[2,3,0,1] row_mask:0xf bank_mask:0xf
	s_nop 1
	s_waitcnt lgkmcnt(0)
	v_add_f32_dpp v55, v55, v55 row_half_mirror row_mask:0xf bank_mask:0xf
	s_nop 1
	s_waitcnt lgkmcnt(0)
; #define LAS __attribute__((address_space(3)))
; __device__ __forceinline__ float bf_lo(unsigned u) { return __uint_as_float(u << 16); }
; __device__ __forceinline__ float bf_hi(unsigned u) { return __uint_as_float(u & 0xffff0000u); }
; __device__ __forceinline__ float bf2f(bf16_t b) { return __uint_as_float((unsigned)b << 16); }
; __device__ __forceinline__ bf16_t f2bf(float f) { return (bf16_t)(pk2(f, 0.f) & 0xffffu); }
; __device__ __forceinline__ float silu_acc(float x) { return x * frcp(1.0f + fexp(-x)); }
; __device__ __forceinline__ void mixer_out_phase(const Ctx& X, LAS unsigned char* lds, int layer, int tid, int wave, int lane) {
;     ...
;         for (int rt = 0; rt < 2; ++rt) {
;             f32x4 acc[4];
;             acc[0] = (f32x4){bf_lo(ov[rt][0].x), bf_hi(ov[rt][0].x), bf_lo(ov[rt][0].y), bf_hi(ov[rt][0].y)}; acc[1] = (f32x4){bf_lo(ov[rt][0].z), bf_hi(ov[rt][0].z), bf_lo(ov[rt][0].w), bf_hi(ov[rt][0].w)};
;             acc[2] = (f32x4){bf_lo(ov[rt][1].x), bf_hi(ov[rt][1].x), bf_lo(ov[rt][1].y), bf_hi(ov[rt][1].y)}; acc[3] = (f32x4){bf_lo(ov[rt][1].z), bf_hi(ov[rt][1].z), bf_lo(ov[rt][1].w), bf_hi(ov[rt][1].w)};
; #pragma unroll
;             for (int ct = 0; ct < 4; ++ct)
; #pragma unroll
;                 for (int ks = 0; ks < 2; ++ks) acc[ct] = __builtin_amdgcn_mfma_f32_16x16x32_bf16(a[rt][ks], bb[ct][ks], acc[ct], 0, 0, 0);
; #pragma unroll
;             for (int j = 0; j < 4; ++j) {
;                 float sm = (acc[0][j] + acc[1][j]) + (acc[2][j] + acc[3][j]);
;                 sm += __shfl_xor(sm, 1); sm += __shfl_xor(sm, 2); sm += __shfl_xor(sm, 4); sm += __shfl_xor(sm, 8);
;                 const float mu = mixer == 0 ? sm * (1.f / 64.f) : 0.f;
;                 float d[4], s2 = 0.f;
; #pragma unroll
;                 for (int ct = 0; ct < 4; ++ct) { d[ct] = acc[ct][j] - mu; s2 += d[ct] * d[ct]; }
;                 s2 += __shfl_xor(s2, 1); s2 += __shfl_xor(s2, 2); s2 += __shfl_xor(s2, 4); s2 += __shfl_xor(s2, 8);
;                 const float rs = rsqrtf(s2 * (1.f / 64.f) + (mixer == 0 ? 1e-5f : 1e-6f));
;                 const int ii = 16 * (2 * half + rt) + 4 * q + j;
; #pragma unroll
;                 for (int ct = 0; ct < 4; ++ct) { LAS bf16_t* gp = GT + ii * GP + h * 64 + 16 * ct + r;
;                     const float y = d[ct] * rs * wv[ct] * silu_acc(bf2f(*gp));
;                     *gp = on ? f2bf(y) : (bf16_t)0; }
	v_add_f32_dpp v55, v55, v55 row_mirror row_mask:0xf bank_mask:0xf
	v_fmamk_f32 v55, v55, 0x3c800000, v107
	v_cmp_gt_f32_e64 s[0:1], s3, v55
	v_mul_f32_e32 v56, 0x4b800000, v55
	s_nop 0
	v_cndmask_b32_e64 v55, v55, v56, s[0:1]
	v_rsq_f32_e32 v55, v55
	s_nop 0
	v_mul_f32_e32 v56, 0x45800000, v55
	v_cndmask_b32_e64 v55, v55, v56, s[0:1]
	v_mov_b32_e32 v56, v142
	s_nop 0
	v_mul_f32_e32 v59, v59, v55
	v_mul_f32_e32 v59, v101, v59
	s_nop 0
	v_lshlrev_b32_e32 v56, 16, v56
	v_mul_f32_e32 v60, 0xbfb8aa3b, v56
	v_exp_f32_e32 v60, v60
	s_nop 0
	v_add_f32_e32 v60, 1.0, v60
	v_rcp_f32_e32 v60, v60
	s_nop 0
	v_mul_f32_e32 v56, v60, v56
	v_mul_f32_e32 v60, v62, v55
	v_mul_f32_e32 v60, v106, v60
	v_mul_f32_e32 v56, v56, v60
	v_cvt_pk_bf16_f32 v56, v56, v157
	ds_write_b16 v54, v56 offset:1056
	v_mov_b32_e32 v56, v143
	s_nop 0
	s_nop 0
	v_lshlrev_b32_e32 v56, 16, v56
	v_mul_f32_e32 v60, 0xbfb8aa3b, v56
	v_exp_f32_e32 v60, v60
	s_nop 0
	v_add_f32_e32 v60, 1.0, v60
	v_rcp_f32_e32 v60, v60
	s_nop 0
	v_mul_f32_e32 v56, v60, v56
	v_mul_f32_e32 v60, v63, v55
	v_mul_f32_e32 v60, v103, v60
	v_mul_f32_e32 v56, v56, v60
	v_cvt_pk_bf16_f32 v56, v56, v157
	ds_write_b16 v54, v56 offset:1088
	v_mov_b32_e32 v56, v144
	s_nop 0
	v_mul_f32_e32 v55, v58, v55
	v_mul_f32_e32 v55, v99, v55
	s_nop 0
	v_lshlrev_b32_e32 v56, 16, v56
	v_mul_f32_e32 v60, 0xbfb8aa3b, v56
	v_exp_f32_e32 v60, v60
	s_nop 0
	v_add_f32_e32 v60, 1.0, v60
	v_rcp_f32_e32 v60, v60
	s_nop 0
	v_mul_f32_e32 v56, v60, v56
	v_mul_f32_e32 v56, v56, v59
	v_cvt_pk_bf16_f32 v56, v56, v157
	ds_write_b16 v54, v56 offset:1120
	v_mov_b32_e32 v56, v145
	s_nop 0
	v_mov_b32_e32 v60, v57
	s_nop 0
	v_lshlrev_b32_e32 v56, 16, v56
	v_mul_f32_e32 v59, 0xbfb8aa3b, v56
	v_exp_f32_e32 v59, v59
	s_nop 0
	v_add_f32_e32 v59, 1.0, v59
	v_rcp_f32_e32 v59, v59
	s_nop 0
	v_mul_f32_e32 v56, v59, v56
	v_mul_f32_e32 v55, v55, v56
	v_cvt_pk_bf16_f32 v55, v55, v157
	v_pk_add_f32 v[58:59], v[60:61], v[68:69]
	ds_write_b16 v54, v55 offset:1152
	v_add_f32_e32 v55, v58, v59
	s_nop 1
	v_mov_b32_e32 v60, v69
	s_waitcnt lgkmcnt(0)
	v_add_f32_dpp v55, v55, v55 quad_perm:[1,0,3,2] row_mask:0xf bank_mask:0xf
	s_nop 1
	s_waitcnt lgkmcnt(0)
	v_add_f32_dpp v55, v55, v55 quad_perm:[2,3,0,1] row_mask:0xf bank_mask:0xf
	s_nop 1
	s_waitcnt lgkmcnt(0)
	v_add_f32_dpp v55, v55, v55 row_half_mirror row_mask:0xf bank_mask:0xf
	s_nop 1
	s_waitcnt lgkmcnt(0)
	v_add_f32_dpp v55, v55, v55 row_mirror row_mask:0xf bank_mask:0xf
	v_mul_f32_e32 v55, 0x3c800000, v55
	v_cndmask_b32_e32 v56, 0, v55, vcc
	v_pk_add_f32 v[58:59], v[64:65], v[56:57] op_sel_hi:[1,0] neg_lo:[0,1] neg_hi:[0,1]
	v_pk_add_f32 v[56:57], v[60:61], v[56:57] op_sel_hi:[1,0] neg_lo:[0,1] neg_hi:[0,1]
	v_pk_mul_f32 v[62:63], v[58:59], v[58:59]
	v_pk_mul_f32 v[60:61], v[56:57], v[56:57]
	v_add_f32_e32 v55, v62, v63
	v_add_f32_e32 v55, v61, v55
	v_add_f32_e32 v55, v60, v55
	s_nop 1
	v_lshlrev_b32_e32 v62, 16, v15
	v_and_b32_e32 v63, 0xffff0000, v15
	v_lshlrev_b32_e32 v64, 16, v16
	v_and_b32_e32 v65, 0xffff0000, v16
	s_waitcnt lgkmcnt(0)
	v_add_f32_dpp v55, v55, v55 quad_perm:[1,0,3,2] row_mask:0xf bank_mask:0xf
	s_nop 1
	s_waitcnt lgkmcnt(0)
	v_add_f32_dpp v55, v55, v55 quad_perm:[2,3,0,1] row_mask:0xf bank_mask:0xf
	s_nop 1
	s_waitcnt lgkmcnt(0)
	v_add_f32_dpp v55, v55, v55 row_half_mirror row_mask:0xf bank_mask:0xf
	s_nop 1
	s_waitcnt lgkmcnt(0)
	v_add_f32_dpp v55, v55, v55 row_mirror row_mask:0xf bank_mask:0xf
	v_fmamk_f32 v55, v55, 0x3c800000, v107
	v_cmp_gt_f32_e64 s[0:1], s3, v55
	v_mul_f32_e32 v60, 0x4b800000, v55
	s_nop 0
	v_cndmask_b32_e64 v55, v55, v60, s[0:1]
	v_rsq_f32_e32 v55, v55
	s_nop 0
	v_mul_f32_e32 v60, 0x45800000, v55
	v_cndmask_b32_e64 v55, v55, v60, s[0:1]
	v_mov_b32_e32 v60, v147
	s_nop 0
	v_mul_f32_e32 v58, v58, v55
	v_mul_f32_e32 v58, v106, v58
	v_mul_f32_e32 v59, v59, v55
	v_mul_f32_e32 v59, v103, v59
	s_nop 0
	v_lshlrev_b32_e32 v60, 16, v60
	v_mul_f32_e32 v61, 0xbfb8aa3b, v60
	v_exp_f32_e32 v61, v61
	v_mul_f32_e32 v57, v57, v55
	v_mul_f32_e32 v57, v101, v57
	v_mul_f32_e32 v55, v56, v55
	v_add_f32_e32 v61, 1.0, v61
	v_rcp_f32_e32 v61, v61
	v_mul_f32_e32 v55, v99, v55
	v_lshlrev_b32_e32 v56, 16, v18
	v_mul_f32_e32 v60, v61, v60
	v_mul_f32_e32 v58, v60, v58
	v_cvt_pk_bf16_f32 v58, v58, v157
	ds_write_b16 v54, v58 offset:1584
	v_mov_b32_e32 v58, v148
	s_nop 0
	v_and_b32_e32 v61, 0xffff0000, v14
	s_nop 0
	v_lshlrev_b32_e32 v58, 16, v58
	v_mul_f32_e32 v60, 0xbfb8aa3b, v58
	v_exp_f32_e32 v60, v60
	s_nop 0
	v_add_f32_e32 v60, 1.0, v60
	v_rcp_f32_e32 v60, v60
	s_nop 0
	v_mul_f32_e32 v58, v60, v58
	v_mul_f32_e32 v58, v58, v59
	v_cvt_pk_bf16_f32 v58, v58, v157
	ds_write_b16 v54, v58 offset:1616
	v_mov_b32_e32 v58, v149
	s_nop 0
	v_lshlrev_b32_e32 v60, 16, v14
	s_nop 0
	v_lshlrev_b32_e32 v58, 16, v58
	v_mul_f32_e32 v59, 0xbfb8aa3b, v58
	v_exp_f32_e32 v59, v59
	s_nop 0
	v_add_f32_e32 v59, 1.0, v59
	v_rcp_f32_e32 v59, v59
	s_nop 0
	v_mul_f32_e32 v58, v59, v58
	v_mul_f32_e32 v57, v58, v57
	v_cvt_pk_bf16_f32 v57, v57, v157
	ds_write_b16 v54, v57 offset:1648
	v_mov_b32_e32 v57, v150
	s_nop 0
	v_and_b32_e32 v59, 0xffff0000, v19
	s_nop 0
	v_lshlrev_b32_e32 v57, 16, v57
	v_mul_f32_e32 v58, 0xbfb8aa3b, v57
	v_exp_f32_e32 v58, v58
	s_nop 0
	v_add_f32_e32 v58, 1.0, v58
	v_rcp_f32_e32 v58, v58
	s_nop 0
	v_mul_f32_e32 v57, v58, v57
	v_mul_f32_e32 v55, v55, v57
	v_and_b32_e32 v57, 0xffff0000, v18
	v_lshlrev_b32_e32 v58, 16, v19
	v_lshlrev_b32_e32 v18, 16, v20
	v_and_b32_e32 v19, 0xffff0000, v20
	v_lshlrev_b32_e32 v20, 16, v21
	v_and_b32_e32 v21, 0xffff0000, v21
	v_mfma_f32_16x16x32_bf16 v[14:17], v[6:9], v[22:25], v[56:59]
	v_cvt_pk_bf16_f32 v55, v55, v157
	ds_write_b16 v54, v55 offset:1680
	v_mfma_f32_16x16x32_bf16 v[18:21], v[6:9], v[30:33], v[18:21]
	v_mfma_f32_16x16x32_bf16 v[22:25], v[10:13], v[34:37], v[18:21]
	v_mfma_f32_16x16x32_bf16 v[18:21], v[6:9], v[38:41], v[60:63]
	v_mfma_f32_16x16x32_bf16 v[6:9], v[6:9], v[46:49], v[64:67]
	v_mfma_f32_16x16x32_bf16 v[14:17], v[10:13], v[26:29], v[14:17]
	v_mfma_f32_16x16x32_bf16 v[18:21], v[10:13], v[42:45], v[18:21]
	v_mfma_f32_16x16x32_bf16 v[6:9], v[10:13], v[50:53], v[6:9]
	s_nop 5
	v_mov_b32_e32 v10, v14
	v_mov_b32_e32 v11, v18
	v_mov_b32_e32 v12, v22
	v_mov_b32_e32 v29, v18
	v_mov_b32_e32 v13, v6
	v_pk_add_f32 v[10:11], v[10:11], v[12:13]
	v_mov_b32_e32 v12, v14
	v_add_f32_e32 v10, v10, v11
	s_nop 1
	v_mov_b32_e32 v13, v22
	v_mov_b32_e32 v28, v6
	v_mov_b32_e32 v22, v15
	s_waitcnt lgkmcnt(0)
; #define LAS __attribute__((address_space(3)))
; __device__ __forceinline__ float bf2f(bf16_t b) { return __uint_as_float((unsigned)b << 16); }
; __device__ __forceinline__ bf16_t f2bf(float f) { return (bf16_t)(pk2(f, 0.f) & 0xffffu); }
; __device__ __forceinline__ float silu_acc(float x) { return x * frcp(1.0f + fexp(-x)); }
; __device__ __forceinline__ void mixer_out_phase(const Ctx& X, LAS unsigned char* lds, int layer, int tid, int wave, int lane) {
;     ...
;             for (int j = 0; j < 4; ++j) {
;                 float sm = (acc[0][j] + acc[1][j]) + (acc[2][j] + acc[3][j]);
;                 sm += __shfl_xor(sm, 1); sm += __shfl_xor(sm, 2); sm += __shfl_xor(sm, 4); sm += __shfl_xor(sm, 8);
;                 const float mu = mixer == 0 ? sm * (1.f / 64.f) : 0.f;
;                 float d[4], s2 = 0.f;
; #pragma unroll
;                 for (int ct = 0; ct < 4; ++ct) { d[ct] = acc[ct][j] - mu; s2 += d[ct] * d[ct]; }
;                 s2 += __shfl_xor(s2, 1); s2 += __shfl_xor(s2, 2); s2 += __shfl_xor(s2, 4); s2 += __shfl_xor(s2, 8);
;                 const float rs = rsqrtf(s2 * (1.f / 64.f) + (mixer == 0 ? 1e-5f : 1e-6f));
;                 const int ii = 16 * (2 * half + rt) + 4 * q + j;
; #pragma unroll
;                 for (int ct = 0; ct < 4; ++ct) { LAS bf16_t* gp = GT + ii * GP + h * 64 + 16 * ct + r;
;                     const float y = d[ct] * rs * wv[ct] * silu_acc(bf2f(*gp));
;                     *gp = on ? f2bf(y) : (bf16_t)0; }
	v_add_f32_dpp v10, v10, v10 quad_perm:[1,0,3,2] row_mask:0xf bank_mask:0xf
	s_nop 1
	s_waitcnt lgkmcnt(0)
	v_add_f32_dpp v10, v10, v10 quad_perm:[2,3,0,1] row_mask:0xf bank_mask:0xf
	s_nop 1
	s_waitcnt lgkmcnt(0)
	v_add_f32_dpp v10, v10, v10 row_half_mirror row_mask:0xf bank_mask:0xf
	s_nop 1
	s_waitcnt lgkmcnt(0)
	v_add_f32_dpp v10, v10, v10 row_mirror row_mask:0xf bank_mask:0xf
	v_mul_f32_e32 v10, 0x3c800000, v10
	v_cndmask_b32_e32 v10, 0, v10, vcc
	v_pk_add_f32 v[12:13], v[12:13], v[10:11] op_sel_hi:[1,0] neg_lo:[0,1] neg_hi:[0,1]
	v_pk_add_f32 v[10:11], v[28:29], v[10:11] op_sel_hi:[1,0] neg_lo:[0,1] neg_hi:[0,1]
	v_pk_mul_f32 v[26:27], v[12:13], v[12:13]
	v_pk_mul_f32 v[28:29], v[10:11], v[10:11]
	v_add_f32_e32 v6, v26, v27
	v_add_f32_e32 v6, v29, v6
	v_add_f32_e32 v6, v28, v6
	s_nop 1
	s_waitcnt lgkmcnt(0)
	v_add_f32_dpp v6, v6, v6 quad_perm:[1,0,3,2] row_mask:0xf bank_mask:0xf
	s_nop 1
	s_waitcnt lgkmcnt(0)
	v_add_f32_dpp v6, v6, v6 quad_perm:[2,3,0,1] row_mask:0xf bank_mask:0xf
	s_nop 1
	s_waitcnt lgkmcnt(0)
	v_add_f32_dpp v6, v6, v6 row_half_mirror row_mask:0xf bank_mask:0xf
	s_nop 1
	s_waitcnt lgkmcnt(0)
	v_add_f32_dpp v6, v6, v6 row_mirror row_mask:0xf bank_mask:0xf
	v_fmamk_f32 v6, v6, 0x3c800000, v107
	v_cmp_gt_f32_e64 s[0:1], s3, v6
	v_mul_f32_e32 v14, 0x4b800000, v6
	s_nop 0
	v_cndmask_b32_e64 v6, v6, v14, s[0:1]
	v_rsq_f32_e32 v6, v6
	s_nop 0
	v_mul_f32_e32 v14, 0x45800000, v6
	v_cndmask_b32_e64 v6, v6, v14, s[0:1]
	v_mov_b32_e32 v14, v151
	s_nop 0
	v_mul_f32_e32 v12, v12, v6
	v_mul_f32_e32 v12, v106, v12
	v_mul_f32_e32 v13, v13, v6
	v_mul_f32_e32 v13, v103, v13
	s_nop 0
	v_lshlrev_b32_e32 v14, 16, v14
	v_mul_f32_e32 v18, 0xbfb8aa3b, v14
	v_exp_f32_e32 v18, v18
	v_mul_f32_e32 v11, v11, v6
	v_mul_f32_e32 v11, v101, v11
	v_mul_f32_e32 v6, v10, v6
	v_add_f32_e32 v18, 1.0, v18
	v_rcp_f32_e32 v18, v18
	v_mul_f32_e32 v6, v99, v6
	v_mul_f32_e32 v14, v18, v14
	v_mul_f32_e32 v12, v14, v12
	v_cvt_pk_bf16_f32 v12, v12, v157
	ds_write_b16 v54, v12 offset:8448
	v_mov_b32_e32 v12, v152
	s_nop 0
	v_mov_b32_e32 v18, v15
	s_nop 0
	v_lshlrev_b32_e32 v12, 16, v12
	v_mul_f32_e32 v14, 0xbfb8aa3b, v12
	v_exp_f32_e32 v14, v14
	s_nop 0
	v_add_f32_e32 v14, 1.0, v14
	v_rcp_f32_e32 v14, v14
	s_nop 0
	v_mul_f32_e32 v12, v14, v12
	v_mul_f32_e32 v12, v12, v13
	v_cvt_pk_bf16_f32 v12, v12, v157
	ds_write_b16 v54, v12 offset:8480
	v_mov_b32_e32 v12, v153
	s_nop 0
	s_nop 0
	v_lshlrev_b32_e32 v12, 16, v12
	v_mul_f32_e32 v13, 0xbfb8aa3b, v12
	v_exp_f32_e32 v13, v13
	s_nop 0
	v_add_f32_e32 v13, 1.0, v13
	v_rcp_f32_e32 v13, v13
	s_nop 0
	v_mul_f32_e32 v12, v13, v12
	v_mul_f32_e32 v11, v12, v11
	v_cvt_pk_bf16_f32 v11, v11, v157
	ds_write_b16 v54, v11 offset:8512
	v_mov_b32_e32 v11, v154
	s_nop 0
	s_nop 0
	v_lshlrev_b32_e32 v11, 16, v11
	v_mul_f32_e32 v12, 0xbfb8aa3b, v11
	v_exp_f32_e32 v12, v12
	s_nop 0
	v_add_f32_e32 v12, 1.0, v12
	v_rcp_f32_e32 v12, v12
	s_nop 0
	v_mul_f32_e32 v11, v12, v11
	v_mul_f32_e32 v6, v11, v6
	v_cvt_pk_bf16_f32 v6, v6, v157
	ds_write_b16 v54, v6 offset:8544
	v_mov_b32_e32 v6, v23
	v_pk_add_f32 v[10:11], v[18:19], v[6:7]
	v_mov_b32_e32 v18, v7
	v_add_f32_e32 v6, v10, v11
	s_nop 1
	s_waitcnt lgkmcnt(0)
	v_add_f32_dpp v6, v6, v6 quad_perm:[1,0,3,2] row_mask:0xf bank_mask:0xf
	s_nop 1
	s_waitcnt lgkmcnt(0)
	v_add_f32_dpp v6, v6, v6 quad_perm:[2,3,0,1] row_mask:0xf bank_mask:0xf
	s_nop 1
	s_waitcnt lgkmcnt(0)
	v_add_f32_dpp v6, v6, v6 row_half_mirror row_mask:0xf bank_mask:0xf
	s_nop 1
	s_waitcnt lgkmcnt(0)
	v_add_f32_dpp v6, v6, v6 row_mirror row_mask:0xf bank_mask:0xf
	v_mul_f32_e32 v6, 0x3c800000, v6
	v_cndmask_b32_e32 v6, 0, v6, vcc
	v_pk_add_f32 v[10:11], v[22:23], v[6:7] op_sel_hi:[1,0] neg_lo:[0,1] neg_hi:[0,1]
	v_pk_add_f32 v[6:7], v[18:19], v[6:7] op_sel_hi:[1,0] neg_lo:[0,1] neg_hi:[0,1]
	v_pk_mul_f32 v[12:13], v[10:11], v[10:11]
	v_pk_mul_f32 v[14:15], v[6:7], v[6:7]
	v_add_f32_e32 v12, v12, v13
	v_add_f32_e32 v12, v15, v12
	v_add_f32_e32 v12, v14, v12
	s_nop 1
	v_mov_b32_e32 v15, v20
	s_waitcnt lgkmcnt(0)
	v_add_f32_dpp v12, v12, v12 quad_perm:[1,0,3,2] row_mask:0xf bank_mask:0xf
	s_nop 1
	s_waitcnt lgkmcnt(0)
	v_add_f32_dpp v12, v12, v12 quad_perm:[2,3,0,1] row_mask:0xf bank_mask:0xf
	s_nop 1
	s_waitcnt lgkmcnt(0)
	v_add_f32_dpp v12, v12, v12 row_half_mirror row_mask:0xf bank_mask:0xf
	s_nop 1
	s_waitcnt lgkmcnt(0)
	v_add_f32_dpp v12, v12, v12 row_mirror row_mask:0xf bank_mask:0xf
	v_fmamk_f32 v12, v12, 0x3c800000, v107
	v_cmp_gt_f32_e64 s[0:1], s3, v12
	v_mul_f32_e32 v13, 0x4b800000, v12
	s_nop 0
	v_cndmask_b32_e64 v12, v12, v13, s[0:1]
	v_rsq_f32_e32 v12, v12
	s_nop 0
	v_mul_f32_e32 v13, 0x45800000, v12
	v_cndmask_b32_e64 v12, v12, v13, s[0:1]
	v_mov_b32_e32 v13, v155
	s_nop 0
	v_mul_f32_e32 v10, v10, v12
	v_mul_f32_e32 v10, v106, v10
	v_mul_f32_e32 v11, v11, v12
	v_mul_f32_e32 v11, v103, v11
	s_nop 0
	v_lshlrev_b32_e32 v13, 16, v13
	v_mul_f32_e32 v14, 0xbfb8aa3b, v13
	v_exp_f32_e32 v14, v14
	v_mul_f32_e32 v7, v7, v12
	v_mul_f32_e32 v7, v101, v7
	v_mul_f32_e32 v6, v6, v12
	v_add_f32_e32 v14, 1.0, v14
	v_rcp_f32_e32 v14, v14
	v_mul_f32_e32 v6, v99, v6
	v_mul_f32_e32 v13, v14, v13
	v_mul_f32_e32 v10, v13, v10
	v_cvt_pk_bf16_f32 v10, v10, v157
	ds_write_b16 v54, v10 offset:8976
	v_mov_b32_e32 v10, v182
	s_nop 0
	v_mov_b32_e32 v14, v8
	s_nop 0
	v_lshlrev_b32_e32 v10, 16, v10
	v_mul_f32_e32 v13, 0xbfb8aa3b, v10
	v_exp_f32_e32 v13, v13
	s_nop 0
	v_add_f32_e32 v13, 1.0, v13
	v_rcp_f32_e32 v13, v13
	s_nop 0
	v_mul_f32_e32 v10, v13, v10
	v_mul_f32_e32 v10, v10, v11
	v_cvt_pk_bf16_f32 v10, v10, v157
	ds_write_b16 v54, v10 offset:9008
	v_mov_b32_e32 v10, v183
	s_nop 0
	s_nop 0
	v_lshlrev_b32_e32 v10, 16, v10
	v_mul_f32_e32 v11, 0xbfb8aa3b, v10
	v_exp_f32_e32 v11, v11
	s_nop 0
	v_add_f32_e32 v11, 1.0, v11
	v_rcp_f32_e32 v11, v11
	s_nop 0
	v_mul_f32_e32 v10, v11, v10
	v_mul_f32_e32 v7, v10, v7
	v_cvt_pk_bf16_f32 v7, v7, v157
	ds_write_b16 v54, v7 offset:9040
	v_mov_b32_e32 v7, v184
	s_nop 0
	v_mov_b32_e32 v11, v8
	s_nop 0
	v_lshlrev_b32_e32 v7, 16, v7
	v_mul_f32_e32 v10, 0xbfb8aa3b, v7
	v_exp_f32_e32 v10, v10
	s_nop 0
	v_add_f32_e32 v10, 1.0, v10
	v_rcp_f32_e32 v10, v10
	s_nop 0
	v_mul_f32_e32 v7, v10, v7
	v_mul_f32_e32 v6, v6, v7
	v_cvt_pk_bf16_f32 v6, v6, v157
	ds_write_b16 v54, v6 offset:9072
	v_mov_b32_e32 v6, v16
	v_mov_b32_e32 v7, v20
	v_mov_b32_e32 v10, v24
	v_pk_add_f32 v[6:7], v[6:7], v[10:11]
	v_mov_b32_e32 v10, v16
	v_add_f32_e32 v6, v6, v7
	s_nop 1
	v_mov_b32_e32 v11, v24
	v_mov_b32_e32 v20, v17
	v_mov_b32_e32 v24, v17
	s_waitcnt lgkmcnt(0)
; #define LAS __attribute__((address_space(3)))
; __device__ __forceinline__ float bf2f(bf16_t b) { return __uint_as_float((unsigned)b << 16); }
; __device__ __forceinline__ bf16_t f2bf(float f) { return (bf16_t)(pk2(f, 0.f) & 0xffffu); }
; __device__ __forceinline__ float silu_acc(float x) { return x * frcp(1.0f + fexp(-x)); }
; __device__ __forceinline__ void mixer_out_phase(const Ctx& X, LAS unsigned char* lds, int layer, int tid, int wave, int lane) {
;     ...
;             for (int j = 0; j < 4; ++j) {
;                 float sm = (acc[0][j] + acc[1][j]) + (acc[2][j] + acc[3][j]);
;                 sm += __shfl_xor(sm, 1); sm += __shfl_xor(sm, 2); sm += __shfl_xor(sm, 4); sm += __shfl_xor(sm, 8);
;                 const float mu = mixer == 0 ? sm * (1.f / 64.f) : 0.f;
;                 float d[4], s2 = 0.f;
; #pragma unroll
;                 for (int ct = 0; ct < 4; ++ct) { d[ct] = acc[ct][j] - mu; s2 += d[ct] * d[ct]; }
;                 s2 += __shfl_xor(s2, 1); s2 += __shfl_xor(s2, 2); s2 += __shfl_xor(s2, 4); s2 += __shfl_xor(s2, 8);
;                 const float rs = rsqrtf(s2 * (1.f / 64.f) + (mixer == 0 ? 1e-5f : 1e-6f));
;                 const int ii = 16 * (2 * half + rt) + 4 * q + j;
; #pragma unroll
;                 for (int ct = 0; ct < 4; ++ct) { LAS bf16_t* gp = GT + ii * GP + h * 64 + 16 * ct + r;
;                     const float y = d[ct] * rs * wv[ct] * silu_acc(bf2f(*gp));
;                     *gp = on ? f2bf(y) : (bf16_t)0; }
	v_add_f32_dpp v6, v6, v6 quad_perm:[1,0,3,2] row_mask:0xf bank_mask:0xf
	s_nop 1
	s_waitcnt lgkmcnt(0)
	v_add_f32_dpp v6, v6, v6 quad_perm:[2,3,0,1] row_mask:0xf bank_mask:0xf
	s_nop 1
	s_waitcnt lgkmcnt(0)
	v_add_f32_dpp v6, v6, v6 row_half_mirror row_mask:0xf bank_mask:0xf
	s_nop 1
	s_waitcnt lgkmcnt(0)
	v_add_f32_dpp v6, v6, v6 row_mirror row_mask:0xf bank_mask:0xf
	v_mul_f32_e32 v6, 0x3c800000, v6
	v_cndmask_b32_e32 v6, 0, v6, vcc
	v_pk_add_f32 v[10:11], v[10:11], v[6:7] op_sel_hi:[1,0] neg_lo:[0,1] neg_hi:[0,1]
	v_pk_add_f32 v[6:7], v[14:15], v[6:7] op_sel_hi:[1,0] neg_lo:[0,1] neg_hi:[0,1]
	v_pk_mul_f32 v[12:13], v[10:11], v[10:11]
	v_pk_mul_f32 v[14:15], v[6:7], v[6:7]
	v_add_f32_e32 v8, v12, v13
	v_add_f32_e32 v8, v15, v8
	v_add_f32_e32 v8, v14, v8
	s_nop 1
	s_waitcnt lgkmcnt(0)
	v_add_f32_dpp v8, v8, v8 quad_perm:[1,0,3,2] row_mask:0xf bank_mask:0xf
	s_nop 1
	s_waitcnt lgkmcnt(0)
	v_add_f32_dpp v8, v8, v8 quad_perm:[2,3,0,1] row_mask:0xf bank_mask:0xf
	s_nop 1
	s_waitcnt lgkmcnt(0)
	v_add_f32_dpp v8, v8, v8 row_half_mirror row_mask:0xf bank_mask:0xf
	s_nop 1
	s_waitcnt lgkmcnt(0)
	v_add_f32_dpp v8, v8, v8 row_mirror row_mask:0xf bank_mask:0xf
	v_fmamk_f32 v8, v8, 0x3c800000, v107
	v_cmp_gt_f32_e64 s[0:1], s3, v8
	v_mul_f32_e32 v12, 0x4b800000, v8
	s_nop 0
	v_cndmask_b32_e64 v8, v8, v12, s[0:1]
	v_rsq_f32_e32 v8, v8
	s_nop 0
	v_mul_f32_e32 v12, 0x45800000, v8
	v_cndmask_b32_e64 v8, v8, v12, s[0:1]
	v_mov_b32_e32 v12, v185
	s_nop 0
	v_mul_f32_e32 v10, v10, v8
	v_mul_f32_e32 v10, v106, v10
	v_mul_f32_e32 v11, v11, v8
	v_mul_f32_e32 v11, v103, v11
	s_nop 0
	v_lshlrev_b32_e32 v12, 16, v12
	v_mul_f32_e32 v13, 0xbfb8aa3b, v12
	v_exp_f32_e32 v13, v13
	v_mul_f32_e32 v7, v7, v8
	v_mul_f32_e32 v7, v101, v7
	v_mul_f32_e32 v6, v6, v8
	v_add_f32_e32 v13, 1.0, v13
	v_rcp_f32_e32 v13, v13
	v_mul_f32_e32 v6, v99, v6
	v_mov_b32_e32 v8, v25
	s_lshl_b32 s0, s11, 1
	v_mul_f32_e32 v12, v13, v12
	v_mul_f32_e32 v10, v12, v10
	v_cvt_pk_bf16_f32 v10, v10, v157
	ds_write_b16 v54, v10 offset:9504
	v_mov_b32_e32 v10, v186
	s_nop 0
	s_add_u32 s0, s60, s0
	s_addc_u32 s1, s67, 0
	s_add_i32 s10, s10, s18
	s_cmpk_lt_i32 s10, 0x600
	s_nop 0
	v_lshlrev_b32_e32 v10, 16, v10
	v_mul_f32_e32 v12, 0xbfb8aa3b, v10
	v_exp_f32_e32 v12, v12
	s_nop 0
	v_add_f32_e32 v12, 1.0, v12
	v_rcp_f32_e32 v12, v12
	s_nop 0
	v_mul_f32_e32 v10, v12, v10
	v_mul_f32_e32 v10, v10, v11
	v_cvt_pk_bf16_f32 v10, v10, v157
	ds_write_b16 v54, v10 offset:9536
	v_mov_b32_e32 v10, v187
	s_nop 0
	s_nop 0
	v_lshlrev_b32_e32 v10, 16, v10
	v_mul_f32_e32 v11, 0xbfb8aa3b, v10
	v_exp_f32_e32 v11, v11
	s_nop 0
	v_add_f32_e32 v11, 1.0, v11
	v_rcp_f32_e32 v11, v11
	s_nop 0
	v_mul_f32_e32 v10, v11, v10
	v_mul_f32_e32 v7, v10, v7
	v_cvt_pk_bf16_f32 v7, v7, v157
	ds_write_b16 v54, v7 offset:9568
	v_mov_b32_e32 v7, v188
	s_nop 0
	s_nop 0
	v_lshlrev_b32_e32 v7, 16, v7
	v_mul_f32_e32 v10, 0xbfb8aa3b, v7
	v_exp_f32_e32 v10, v10
	s_nop 0
	v_add_f32_e32 v10, 1.0, v10
	v_rcp_f32_e32 v10, v10
	s_nop 0
	v_mul_f32_e32 v7, v10, v7
	v_mul_f32_e32 v6, v6, v7
	v_cvt_pk_bf16_f32 v6, v6, v157
	ds_write_b16 v54, v6 offset:9600
	v_pk_add_f32 v[6:7], v[20:21], v[8:9]
	v_mov_b32_e32 v20, v9
	v_add_f32_e32 v6, v6, v7
	s_nop 1
	s_waitcnt lgkmcnt(0)
	v_add_f32_dpp v6, v6, v6 quad_perm:[1,0,3,2] row_mask:0xf bank_mask:0xf
	s_nop 1
	s_waitcnt lgkmcnt(0)
	v_add_f32_dpp v6, v6, v6 quad_perm:[2,3,0,1] row_mask:0xf bank_mask:0xf
	s_nop 1
	s_waitcnt lgkmcnt(0)
	v_add_f32_dpp v6, v6, v6 row_half_mirror row_mask:0xf bank_mask:0xf
	s_nop 1
	s_waitcnt lgkmcnt(0)
	v_add_f32_dpp v6, v6, v6 row_mirror row_mask:0xf bank_mask:0xf
	v_mul_f32_e32 v6, 0x3c800000, v6
	v_cndmask_b32_e32 v6, 0, v6, vcc
	v_pk_add_f32 v[10:11], v[24:25], v[6:7] op_sel_hi:[1,0] neg_lo:[0,1] neg_hi:[0,1]
	v_pk_add_f32 v[6:7], v[20:21], v[6:7] op_sel_hi:[1,0] neg_lo:[0,1] neg_hi:[0,1]
	v_pk_mul_f32 v[12:13], v[10:11], v[10:11]
	v_pk_mul_f32 v[8:9], v[6:7], v[6:7]
	v_add_f32_e32 v12, v12, v13
	v_add_f32_e32 v9, v9, v12
	v_add_f32_e32 v8, v8, v9
	s_nop 1
	s_waitcnt lgkmcnt(0)
	v_add_f32_dpp v8, v8, v8 quad_perm:[1,0,3,2] row_mask:0xf bank_mask:0xf
	s_nop 1
	s_waitcnt lgkmcnt(0)
	v_add_f32_dpp v8, v8, v8 quad_perm:[2,3,0,1] row_mask:0xf bank_mask:0xf
	s_nop 1
	s_waitcnt lgkmcnt(0)
	v_add_f32_dpp v8, v8, v8 row_half_mirror row_mask:0xf bank_mask:0xf
	s_nop 1
	s_waitcnt lgkmcnt(0)
	v_add_f32_dpp v8, v8, v8 row_mirror row_mask:0xf bank_mask:0xf
	v_fmac_f32_e32 v107, 0x3c800000, v8
	v_cmp_gt_f32_e32 vcc, s3, v107
	v_mul_f32_e32 v8, 0x4b800000, v107
	s_nop 0
	v_cndmask_b32_e32 v8, v107, v8, vcc
	v_rsq_f32_e32 v8, v8
	s_nop 0
	v_mul_f32_e32 v9, 0x45800000, v8
	v_cndmask_b32_e32 v8, v8, v9, vcc
	v_mov_b32_e32 v9, v189
	s_nop 0
	v_mul_f32_e32 v10, v10, v8
	v_mul_f32_e32 v10, v106, v10
	v_mul_f32_e32 v7, v7, v8
	v_mul_f32_e32 v7, v101, v7
	s_nop 0
	v_lshlrev_b32_e32 v9, 16, v9
	v_mul_f32_e32 v12, 0xbfb8aa3b, v9
	v_exp_f32_e32 v12, v12
	v_mul_f32_e32 v6, v6, v8
	v_mul_f32_e32 v6, v99, v6
	v_add_f32_e32 v12, 1.0, v12
	v_rcp_f32_e32 v12, v12
	s_nop 0
	v_mul_f32_e32 v9, v12, v9
	v_mul_f32_e32 v9, v9, v10
	v_cvt_pk_bf16_f32 v9, v9, v157
	ds_write_b16 v54, v9 offset:10032
	v_mov_b32_e32 v9, v190
	s_nop 0
	v_lshlrev_b64 v[12:13], 11, v[92:93]
	s_nop 0
	v_lshlrev_b32_e32 v9, 16, v9
	v_mul_f32_e32 v10, 0xbfb8aa3b, v9
	v_exp_f32_e32 v10, v10
	s_nop 0
	v_add_f32_e32 v10, 1.0, v10
	v_rcp_f32_e32 v10, v10
	s_nop 0
	v_mul_f32_e32 v9, v10, v9
	v_mul_f32_e32 v10, v11, v8
	v_mul_f32_e32 v10, v103, v10
	v_mul_f32_e32 v9, v9, v10
	v_cvt_pk_bf16_f32 v9, v9, v157
	ds_write_b16 v54, v9 offset:10064
	v_mov_b32_e32 v9, v191
	s_nop 0
	s_nop 0
	v_lshlrev_b32_e32 v9, 16, v9
	v_mul_f32_e32 v10, 0xbfb8aa3b, v9
	v_exp_f32_e32 v10, v10
	s_nop 0
	v_add_f32_e32 v10, 1.0, v10
	v_rcp_f32_e32 v10, v10
	s_nop 0
	v_mul_f32_e32 v9, v10, v9
	v_mul_f32_e32 v7, v9, v7
	v_cvt_pk_bf16_f32 v7, v7, v157
	ds_write_b16 v54, v7 offset:10096
	v_mov_b32_e32 v7, v192
	s_nop 0
	v_lshl_add_u64 v[10:11], s[0:1], 0, v[156:157]
	v_lshl_add_u64 v[12:13], v[10:11], 0, v[12:13]
	s_nop 0
	v_lshlrev_b32_e32 v7, 16, v7
	v_mul_f32_e32 v9, 0xbfb8aa3b, v7
	v_exp_f32_e32 v9, v9
	s_nop 0
	v_add_f32_e32 v9, 1.0, v9
	v_rcp_f32_e32 v9, v9
	s_nop 0
	v_mul_f32_e32 v7, v9, v7
	v_mul_f32_e32 v6, v6, v7
	v_cvt_pk_bf16_f32 v6, v6, v157
	ds_write_b16 v54, v6 offset:10128
	s_waitcnt lgkmcnt(0)
	s_barrier
; #define LAS __attribute__((address_space(3)))
; #define LBAR() do { asm volatile("s_waitcnt lgkmcnt(0)" ::: "memory"); __builtin_amdgcn_s_barrier(); asm volatile("" ::: "memory"); } while (0)
; __device__ __forceinline__ void mixer_out_phase(const Ctx& X, LAS unsigned char* lds, int layer, int tid, int wave, int lane) {
;     ...
;         LBAR();
; #pragma unroll
;         for (int n = 0; n < 4; ++n) { const int idx = tid + 512 * n; __builtin_nontemporal_store(*(const LAS u32x4*)(GT + (idx >> 5) * GP + (idx & 31) * 8), (u32x4*)(mix + (row0 + (idx >> 5)) * D + moff + (idx & 31) * 8)); }
;         LBAR();
;     }
	ds_read_b128 v[6:9], v96
	s_waitcnt lgkmcnt(0)
	global_store_dwordx4 v[12:13], v[6:9], off nt
	ds_read_b128 v[6:9], v94
	v_lshlrev_b64 v[12:13], 11, v[90:91]
	v_lshl_add_u64 v[12:13], v[10:11], 0, v[12:13]
	s_waitcnt lgkmcnt(0)
	global_store_dwordx4 v[12:13], v[6:9], off nt
	ds_read_b128 v[6:9], v76
	v_lshlrev_b64 v[12:13], 11, v[88:89]
	v_lshl_add_u64 v[12:13], v[10:11], 0, v[12:13]
	s_waitcnt lgkmcnt(0)
	global_store_dwordx4 v[12:13], v[6:9], off nt
	ds_read_b128 v[6:9], v74
	v_lshlrev_b64 v[12:13], 11, v[86:87]
	v_lshl_add_u64 v[10:11], v[10:11], 0, v[12:13]
	s_waitcnt lgkmcnt(0)
	global_store_dwordx4 v[10:11], v[6:9], off nt
	s_waitcnt lgkmcnt(0)
	s_barrier
	s_cbranch_scc1 .LBB0_888
	v_readlane_b32 s54, v255, 7
	v_readlane_b32 s56, v255, 9
	v_readlane_b32 s58, v255, 11
	v_readlane_b32 s48, v255, 13
	v_readlane_b32 s50, v255, 15
	v_readlane_b32 s52, v255, 17
	v_readlane_b32 s55, v255, 8
	v_readlane_b32 s57, v255, 10
	v_readlane_b32 s59, v255, 12
	v_readlane_b32 s49, v255, 14
	v_readlane_b32 s51, v255, 16
	v_readlane_b32 s53, v255, 18
	s_mov_b64 s[22:23], s[64:65]
	v_readlane_b32 s19, v255, 26
